# attention: next-tile K fragments (d0,d1) prefetched before the barrier; tile DMA issued at top of iteration, waited at its end (on top of S2 hand schedule)
# baseline (speedup 1.0000x reference)
; DI void attn_unit(const Params& p, int bh, int qb, char* lds, float lam, int tid, int lane, int wid, const bool build_tab) {
;     ...
;     for (int t = 0; t < NT; ++t) {
;         const bool act = t < ntw;
;         const lds_cptr vp = (lds_cptr)lds + sc + 16384 + ((lane >> 4) & 1) * 32 + (lane & 3) * 8 + (4 * hi + ((lane & 15) >> 2)) * 64;
;         bf16x8 pf[4]; s16x4 va[8], vb[8];
;         if (act) {
;             const lds_cptr kp = (lds_cptr)lds + sc + map * 8192 + hi * 1024 + r32 * 16;
;             bf16x8 kf[8];
; #pragma unroll
;             for (int d0 = 0; d0 < 4; ++d0) {
;                 kf[2 * d0] = *(const __attribute__((address_space(3))) bf16x8*)(kp + d0 * 2048);
;                 kf[2 * d0 + 1] = *(const __attribute__((address_space(3))) bf16x8*)(kp + d0 * 2048 + 512);
;             }
;             f32x16 s0 = cinit, s1 = cinit;
; #pragma unroll
;             for (int d0 = 0; d0 < 4; ++d0) { s0 = MFMA32(kf[2 * d0], qf[d0], s0); s1 = MFMA32(kf[2 * d0 + 1], qf[d0], s1); }
;             LOADV(va, 0);
;             if (t >= 2 * qb - 2) {
;                 const float* tb = tab + (64 * t - (qrow0 + r32) + 256 + 4 * hi);
; #pragma unroll
;                 for (int i = 0; i < 16; ++i) {
;                     s0[i] += tb[(i & 3) + 8 * (i >> 2)];
;                     s1[i] += tb[(i & 3) + 8 * (i >> 2) + 32];
;                 }
;             }
;             float mxa = MX3(s0[0], s0[1], s1[0]), mxb = MX3(s0[2], s0[3], s1[1]); mxa = MX3(mxa, s1[2], s1[3]);
; #pragma unroll
;             for (int r = 4; r < 16; r += 4) { mxa = MX3(mxa, s0[r], s0[r + 1]); mxb = MX3(mxb, s0[r + 2], s0[r + 3]); mxa = MX3(mxa, s1[r], s1[r + 1]); mxb = MX3(mxb, s1[r + 2], s1[r + 3]); }
;             float mx = swap_max(__builtin_fmaxf(mxa, mxb));
;             const bool first = (t == 0);
;             if (first || __builtin_amdgcn_ballot_w64(mx > 8.0f) != 0ull) {
;                 const float dl = first ? mx : __builtin_fmaxf(mx, 0.f);
;                 const float f = first ? 1.0f : ex2(-dl);
;                 l *= f; nm -= dl;
; #pragma unroll
;                 for (int i = 0; i < 16; ++i) { o[0][i] *= f; o[1][i] *= f; o[2][i] *= f; o[3][i] *= f; cinit[i] = nm; s0[i] -= dl; s1[i] -= dl; }
;             }
;             asm volatile("s_waitcnt vmcnt(0)" ::: "memory");
;             if (t + 2 < NT) GLOAD(t + 2, sn2);
.LBB0_350:
	s_or_b64 exec, exec, s[54:55]
	s_waitcnt vmcnt(0)
	s_waitcnt lgkmcnt(0)
	s_barrier
	ds_read_b128 v[0:3], v216
	ds_read_b128 v[16:19], v216 offset:512
	s_waitcnt vmcnt(3) lgkmcnt(1)
	v_mfma_f32_32x32x16_bf16 v[0:15], v[0:3], v[112:115], 0
	v_lshl_add_u64 v[178:179], v[184:185], 0, s[22:23]
	s_add_i32 s55, s60, 0x10000
	v_lshl_add_u64 v[180:181], v[184:185], 0, s[24:25]
	s_add_i32 s56, s60, 0x12000
	v_lshl_add_u64 v[176:177], v[182:183], 0, s[22:23]
	s_add_i32 s57, s60, 0x14000
	v_lshl_add_u64 v[190:191], v[182:183], 0, s[24:25]
	s_waitcnt lgkmcnt(0)
	v_mfma_f32_32x32x16_bf16 v[64:79], v[16:19], v[112:115], 0
	ds_read_b128 v[16:19], v216 offset:2048
	ds_read_b128 v[20:23], v216 offset:2560
	s_add_i32 s70, s60, 0x16000
	s_lshl_b32 s77, s81, 1
	s_add_i32 s78, s35, s77
	s_lshr_b32 s54, s65, 3
	s_add_i32 s78, s78, 1
	s_add_i32 s79, s77, -2
	s_waitcnt vmcnt(2) lgkmcnt(1)
	v_mfma_f32_32x32x16_bf16 v[0:15], v[16:19], v[116:119], v[0:15]
	s_mov_b32 s80, 0x10000
	s_waitcnt lgkmcnt(0)
	v_mfma_f32_32x32x16_bf16 v[64:79], v[20:23], v[116:119], v[64:79]
	ds_read_b128 v[16:19], v216 offset:4096
	ds_read_b128 v[20:23], v216 offset:4608
	s_waitcnt vmcnt(1) lgkmcnt(1)
	v_mfma_f32_32x32x16_bf16 v[0:15], v[16:19], v[120:123], v[0:15]
	s_waitcnt lgkmcnt(0)
	v_mfma_f32_32x32x16_bf16 v[64:79], v[20:23], v[120:123], v[64:79]
	ds_read_b128 v[16:19], v216 offset:6144
	ds_read_b128 v[20:23], v216 offset:6656
	ds_read_b64_tr_b16 v[24:25], v217 offset:16384
	ds_read_b64_tr_b16 v[26:27], v217 offset:16896
	ds_read_b64_tr_b16 v[28:29], v217 offset:20480
	ds_read_b64_tr_b16 v[30:31], v217 offset:20992
	s_waitcnt vmcnt(0) lgkmcnt(5)
	v_mfma_f32_32x32x16_bf16 v[0:15], v[16:19], v[124:127], v[0:15]
	ds_read_b64_tr_b16 v[16:17], v217 offset:24576
	ds_read_b64_tr_b16 v[18:19], v217 offset:25088
	ds_read_b64_tr_b16 v[96:97], v217 offset:28672
	ds_read_b64_tr_b16 v[98:99], v217 offset:29184
	s_waitcnt vmcnt(0)
	s_mov_b32 s7, m0
	s_mov_b32 m0, s55
	s_nop 0
	global_load_lds_dwordx4 v[178:179], off
	s_mov_b32 m0, s7
	s_nop 7
	v_max_f32_e32 v32, v1, v1
	s_waitcnt lgkmcnt(8)
	v_mfma_f32_32x32x16_bf16 v[64:79], v[20:23], v[124:127], v[64:79]
	v_max_f32_e32 v33, v0, v0
	v_max_f32_e32 v32, v33, v32
	s_mov_b32 s7, m0
	s_mov_b32 m0, s56
	s_nop 0
	global_load_lds_dwordx4 v[180:181], off
	s_mov_b32 m0, s7
	s_nop 0
	s_mov_b32 s7, m0
	s_mov_b32 m0, s57
	s_nop 0
	global_load_lds_dwordx4 v[176:177], off
	s_mov_b32 m0, s7
	s_nop 8
	v_max3_f32 v20, v2, v3, v65
	v_max3_f32 v21, v32, v64, v66
	v_max3_f32 v21, v21, v67, v4
	v_max3_f32 v20, v20, v6, v7
	v_max3_f32 v21, v21, v5, v68
	v_max3_f32 v20, v20, v70, v71
	v_max3_f32 v21, v21, v69, v8
	v_max3_f32 v20, v20, v10, v11
	v_max3_f32 v21, v21, v9, v72
	v_max3_f32 v20, v20, v74, v75
	v_max3_f32 v21, v21, v73, v12
	v_max3_f32 v20, v20, v14, v15
	v_max3_f32 v21, v21, v13, v76
	v_max3_f32 v20, v20, v78, v79
	v_max3_f32 v20, v21, v77, v20
	v_mov_b32_e32 v21, v20
	s_nop 1
	v_permlane32_swap_b32_e32 v20, v21
	v_max_f32_e32 v21, v21, v21
	v_max_f32_e32 v20, v20, v20
	v_max_f32_e32 v146, v20, v21
	v_sub_f32_e32 v0, v0, v146
	v_sub_f32_e32 v1, v1, v146
	v_sub_f32_e32 v2, v2, v146
	v_sub_f32_e32 v3, v3, v146
	v_sub_f32_e32 v4, v4, v146
	v_sub_f32_e32 v5, v5, v146
	v_sub_f32_e32 v6, v6, v146
	v_sub_f32_e32 v7, v7, v146
	v_exp_f32_e32 v94, v0
	v_exp_f32_e32 v92, v1
	v_exp_f32_e32 v90, v2
	v_exp_f32_e32 v88, v3
	v_exp_f32_e32 v86, v4
	v_exp_f32_e32 v84, v5
	v_exp_f32_e32 v82, v6
	v_exp_f32_e32 v80, v7
	v_cvt_pk_bf16_f32 v0, v94, v92
	v_cvt_pk_bf16_f32 v1, v90, v88
	v_cvt_pk_bf16_f32 v2, v86, v84
	v_cvt_pk_bf16_f32 v3, v82, v80
	v_sub_f32_e32 v81, v8, v146
	v_sub_f32_e32 v83, v9, v146
	s_waitcnt lgkmcnt(6)
	v_mfma_f32_32x32x16_bf16 v[48:63], v[24:27], v[0:3], 0
	v_sub_f32_e32 v85, v10, v146
	v_sub_f32_e32 v87, v11, v146
	v_sub_f32_e32 v104, v12, v146
	v_sub_f32_e32 v105, v13, v146
	v_sub_f32_e32 v106, v14, v146
	v_sub_f32_e32 v107, v15, v146
	s_mov_b32 s7, m0
	s_mov_b32 m0, s70
	s_nop 0
	global_load_lds_dwordx4 v[190:191], off
	s_mov_b32 m0, s7
	ds_read_b64_tr_b16 v[100:101], v217 offset:17408
	ds_read_b64_tr_b16 v[102:103], v217 offset:17920
	v_exp_f32_e32 v95, v81
	v_exp_f32_e32 v93, v83
	v_exp_f32_e32 v91, v85
	v_exp_f32_e32 v89, v87
	v_exp_f32_e32 v87, v104
	v_exp_f32_e32 v85, v105
	v_exp_f32_e32 v83, v106
	v_exp_f32_e32 v81, v107
	s_waitcnt lgkmcnt(6)
	v_mfma_f32_32x32x16_bf16 v[32:47], v[28:31], v[0:3], 0
	ds_read_b64_tr_b16 v[104:105], v217 offset:18432
	ds_read_b64_tr_b16 v[106:107], v217 offset:18944
	v_sub_f32_e32 v64, v64, v146
	v_sub_f32_e32 v65, v65, v146
	v_sub_f32_e32 v68, v68, v146
	v_sub_f32_e32 v69, v69, v146
	v_sub_f32_e32 v70, v70, v146
	v_sub_f32_e32 v71, v71, v146
	s_waitcnt lgkmcnt(6)
	v_mfma_f32_32x32x16_bf16 v[16:31], v[16:19], v[0:3], 0
	v_exp_f32_e32 v110, v64
	v_exp_f32_e32 v138, v68
	v_exp_f32_e32 v140, v69
	v_exp_f32_e32 v142, v70
	v_exp_f32_e32 v174, v71
	v_sub_f32_e32 v64, v72, v146
	v_cvt_pk_bf16_f32 v70, v138, v140
	s_waitcnt lgkmcnt(4)
; #define GLOAD(t_, slotoff_) do { const char* kb_ = KGc + ((size_t)(t_) << 14); const char* vb_ = VGc + ((size_t)(t_) << 14); \
;         const unsigned d_ = (unsigned)__builtin_amdgcn_readfirstlane((int)(ldsbase + (slotoff_) + wid * 1024)); \
;         GLDS16(kb_, d_); GLDS16(kb_ + 8192, d_ + 8192u); GLDS16(vb_, d_ + 16384u); GLDS16(vb_ + 8192, d_ + 24576u); } while (0)
; #define SCHEDB() __builtin_amdgcn_sched_barrier(0)
; #define LOADV(dst, ks_) do { _Pragma("unroll") for (int dvb = 0; dvb < 4; ++dvb) { dst[2 * dvb] = vtr(vp + dvb * 4096 + (ks_) * 1024); dst[2 * dvb + 1] = vtr(vp + dvb * 4096 + (ks_) * 1024 + 512); } } while (0)
; #define MF4(src, pfrag) do { _Pragma("unroll") for (int dvb = 0; dvb < 4; ++dvb) { \
;         const bf16x8 vf_ = __builtin_shufflevector(src[2 * dvb], src[2 * dvb + 1], 0, 1, 2, 3, 4, 5, 6, 7); o[dvb] = MFMA32(vf_, pfrag, o[dvb]); } } while (0)
; DI void attn_unit(const Params& p, int bh, int qb, char* lds, float lam, int tid, int lane, int wid, const bool build_tab) {
;     ...
;             const lds_cptr kp = (lds_cptr)lds + sc + map * 8192 + hi * 1024 + r32 * 16;
;             bf16x8 kf[8];
; #pragma unroll
;             for (int d0 = 0; d0 < 4; ++d0) {
;                 kf[2 * d0] = *(const __attribute__((address_space(3))) bf16x8*)(kp + d0 * 2048);
;                 kf[2 * d0 + 1] = *(const __attribute__((address_space(3))) bf16x8*)(kp + d0 * 2048 + 512);
;     ...
;             EXPQ(s0, 0, rs0, pf[0]);
;             LOADV(vb, 1);
;             MF4(va, pf[0]);
;             EXPQ(s0, 8, rs1, pf[1]);
;             LOADV(va, 2);
;             MF4(vb, pf[1]);
;             EXPQ(s1, 0, rs0, pf[2]);
;             LOADV(vb, 3);
;             MF4(va, pf[2]);
;             EXPQ(s1, 8, rs1, pf[3]);
;             MF4(vb, pf[3]);
;             l += rs0 + rs1;
;     ...
;         } else {
;             asm volatile("s_waitcnt vmcnt(0)" ::: "memory");
;             if (t + 2 < NT) GLOAD(t + 2, sn2);
;         }
;         SCHEDB();
;         __builtin_amdgcn_s_barrier();
;         SCHEDB();
;         { const int tmp = sc; sc = sn1; sn1 = sn2; sn2 = tmp; }
	v_mfma_f32_32x32x16_bf16 v[0:15], v[96:99], v[0:3], 0
	v_cvt_pk_bf16_f32 v96, v95, v93
	v_cvt_pk_bf16_f32 v97, v91, v89
	v_cvt_pk_bf16_f32 v98, v87, v85
	v_cvt_pk_bf16_f32 v99, v83, v81
	v_cvt_pk_bf16_f32 v71, v142, v174
	v_exp_f32_e32 v111, v64
	v_sub_f32_e32 v76, v76, v146
	s_waitcnt lgkmcnt(2)
	v_mfma_f32_32x32x16_bf16 v[48:63], v[100:103], v[96:99], v[48:63]
	ds_read_b64_tr_b16 v[100:101], v217 offset:21504
	ds_read_b64_tr_b16 v[102:103], v217 offset:22016
	ds_read_b64_tr_b16 v[108:109], v217 offset:19968
	v_sub_f32_e32 v77, v77, v146
	v_sub_f32_e32 v78, v78, v146
	v_sub_f32_e32 v79, v79, v146
	v_exp_f32_e32 v139, v76
	v_exp_f32_e32 v141, v77
	v_exp_f32_e32 v143, v78
	s_waitcnt lgkmcnt(1)
	v_mfma_f32_32x32x16_bf16 v[32:47], v[100:103], v[96:99], v[32:47]
	ds_read_b64_tr_b16 v[100:101], v217 offset:25600
	ds_read_b64_tr_b16 v[102:103], v217 offset:26112
	ds_read_b64_tr_b16 v[128:129], v217 offset:29696
	ds_read_b64_tr_b16 v[130:131], v217 offset:30208
	ds_read_b64_tr_b16 v[132:133], v217 offset:26624
	ds_read_b64_tr_b16 v[134:135], v217 offset:27136
	v_exp_f32_e32 v175, v79
	s_lshl_b32 s7, s62, 22
	s_and_b32 s82, s7, 0x3800000
	s_mov_b32 s7, 1
	s_waitcnt lgkmcnt(4)
	v_mfma_f32_32x32x16_bf16 v[16:31], v[100:103], v[96:99], v[16:31]
	v_sub_f32_e32 v100, v66, v146
	v_sub_f32_e32 v101, v67, v146
	v_exp_f32_e32 v136, v101
	ds_read_b64_tr_b16 v[66:67], v217 offset:28160
	s_waitcnt lgkmcnt(3)
	v_mfma_f32_32x32x16_bf16 v[0:15], v[128:131], v[96:99], v[0:15]
	v_exp_f32_e32 v128, v65
	v_exp_f32_e32 v130, v100
	ds_read_b64_tr_b16 v[96:97], v217 offset:22528
	ds_read_b64_tr_b16 v[98:99], v217 offset:23040
	ds_read_b64_tr_b16 v[100:101], v217 offset:23552
	ds_read_b64_tr_b16 v[102:103], v217 offset:24064
	v_sub_f32_e32 v65, v73, v146
	v_cvt_pk_bf16_f32 v68, v110, v128
	v_cvt_pk_bf16_f32 v69, v130, v136
	v_exp_f32_e32 v129, v65
	s_nop 0
	v_mfma_f32_32x32x16_bf16 v[48:63], v[104:107], v[68:71], v[48:63]
	ds_read_b64_tr_b16 v[106:107], v217 offset:19456
	v_sub_f32_e32 v104, v74, v146
	v_sub_f32_e32 v105, v75, v146
	v_exp_f32_e32 v131, v104
	v_exp_f32_e32 v137, v105
	s_waitcnt lgkmcnt(3)
	v_mfma_f32_32x32x16_bf16 v[32:47], v[96:99], v[68:71], v[32:47]
	ds_read_b64_tr_b16 v[96:97], v217 offset:30720
	ds_read_b64_tr_b16 v[98:99], v217 offset:31232
	ds_read_b64_tr_b16 v[72:73], v217 offset:31744
	ds_read_b64_tr_b16 v[74:75], v217 offset:32256
	ds_read_b64_tr_b16 v[64:65], v217 offset:27648
	v_mfma_f32_32x32x16_bf16 v[16:31], v[132:135], v[68:71], v[16:31]
	s_waitcnt lgkmcnt(3)
	v_mfma_f32_32x32x16_bf16 v[0:15], v[96:99], v[68:71], v[0:15]
	v_cvt_pk_bf16_f32 v68, v111, v129
	v_cvt_pk_bf16_f32 v69, v131, v137
	v_cvt_pk_bf16_f32 v70, v139, v141
	v_cvt_pk_bf16_f32 v71, v143, v175
	s_waitcnt lgkmcnt(0)
	s_nop 0
	v_mfma_f32_32x32x16_bf16 v[16:31], v[64:67], v[68:71], v[16:31]
	v_add_f32_e64 v66, v94, 0
	v_add_f32_e64 v67, v95, 0
	v_sub_f32_e32 v64, 0, v146
	v_add_f32_e64 v66, v92, v66
	v_add_f32_e64 v67, v93, v67
	v_pk_add_f32 v[66:67], v[90:91], v[66:67]
	s_nop 0
	v_pk_add_f32 v[66:67], v[88:89], v[66:67]
	v_mfma_f32_32x32x16_bf16 v[48:63], v[106:109], v[68:71], v[48:63]
	v_add_f32_e64 v66, v86, v66
	v_add_f32_e64 v67, v87, v67
	v_add_f32_e64 v66, v84, v66
	v_add_f32_e64 v67, v85, v67
	v_add_f32_e64 v66, v82, v66
	v_add_f32_e64 v67, v83, v67
	v_pk_add_f32 v[66:67], v[80:81], v[66:67]
	v_mfma_f32_32x32x16_bf16 v[32:47], v[100:103], v[68:71], v[32:47]
	v_add_f32_e64 v66, v110, v66
	v_add_f32_e64 v67, v111, v67
	v_add_f32_e64 v66, v128, v66
	v_add_f32_e64 v67, v129, v67
	v_add_f32_e64 v66, v130, v66
	v_add_f32_e64 v67, v131, v67
	v_pk_add_f32 v[66:67], v[136:137], v[66:67]
	v_mfma_f32_32x32x16_bf16 v[0:15], v[72:75], v[68:71], v[0:15]
	v_add_f32_e64 v66, v138, v66
	v_add_f32_e64 v67, v139, v67
	v_add_f32_e64 v66, v140, v66
	v_add_f32_e64 v67, v141, v67
	v_add_f32_e64 v66, v142, v66
	v_add_f32_e64 v67, v143, v67
	v_pk_add_f32 v[66:67], v[174:175], v[66:67]
	s_nop 0
	v_add_f32_e32 v65, v66, v67
	v_add_f32_e32 v146, 0, v65
	s_waitcnt vmcnt(0)
	s_add_i32 s96, s61, 0x8000
	v_add3_u32 v221, s96, v204, v205
	ds_read_b128 v[222:225], v221
	ds_read_b128 v[226:229], v221 offset:512
	ds_read_b128 v[230:233], v221 offset:2048
	ds_read_b128 v[234:237], v221 offset:2560
	s_barrier
	s_ashr_i32 s51, s50, 31
	s_lshl_b64 s[50:51], s[50:51], 22
	s_add_u32 s50, s82, s50
	s_addc_u32 s51, 0, s51
	v_lshl_add_u64 v[174:175], v[172:173], 0, s[50:51]
	v_lshl_add_u64 v[174:175], v[174:175], 0, s[94:95]
	s_lshl_b32 s81, s81, 9
	v_subrev_u32_e32 v219, s81, v212
	s_mov_b32 s82, 0
	s_mov_b32 s50, 0x8000
	s_movk_i32 s83, 0xff00
	v_mov_b64_e32 v[200:201], v[174:175]
	v_mov_b32_e32 v65, v64
	v_mov_b32_e32 v66, v64
	v_mov_b32_e32 v67, v64
	v_mov_b32_e32 v68, v64
	v_mov_b32_e32 v69, v64
	v_mov_b32_e32 v70, v64
	v_mov_b32_e32 v71, v64
	v_mov_b32_e32 v72, v64
	v_mov_b32_e32 v73, v64
	v_mov_b32_e32 v74, v64
	v_mov_b32_e32 v75, v64
	v_mov_b32_e32 v76, v64
	v_mov_b32_e32 v77, v64
	v_mov_b32_e32 v78, v64
	v_mov_b32_e32 v79, v64
	s_mov_b32 s84, s50
	s_cmp_ge_u32 s7, s78
	s_mov_b64 s[50:51], -1
	s_cbranch_scc0 .LBB0_352

; DI float ex2(float x) { return __builtin_amdgcn_exp2f(x); }
; DI float swap_max(float m) { auto rr = __builtin_amdgcn_permlane32_swap(__float_as_uint(m), __float_as_uint(m), false, false); return __builtin_fmaxf(__uint_as_float(rr[0]), __uint_as_float(rr[1])); }
; DI void attn_unit(const Params& p, int bh, int qb, char* lds, float lam, int tid, int lane, int wid, const bool build_tab) {
;     ...
;             const lds_cptr kp = (lds_cptr)lds + sc + map * 8192 + hi * 1024 + r32 * 16;
;             bf16x8 kf[8];
; #pragma unroll
;             for (int d0 = 0; d0 < 4; ++d0) {
;                 kf[2 * d0] = *(const __attribute__((address_space(3))) bf16x8*)(kp + d0 * 2048);
;                 kf[2 * d0 + 1] = *(const __attribute__((address_space(3))) bf16x8*)(kp + d0 * 2048 + 512);
;             }
;             f32x16 s0 = cinit, s1 = cinit;
; #pragma unroll
;             for (int d0 = 0; d0 < 4; ++d0) { s0 = MFMA32(kf[2 * d0], qf[d0], s0); s1 = MFMA32(kf[2 * d0 + 1], qf[d0], s1); }
;             LOADV(va, 0);
;             if (t >= 2 * qb - 2) {
;                 const float* tb = tab + (64 * t - (qrow0 + r32) + 256 + 4 * hi);
; #pragma unroll
;                 for (int i = 0; i < 16; ++i) {
;                     s0[i] += tb[(i & 3) + 8 * (i >> 2)];
;                     s1[i] += tb[(i & 3) + 8 * (i >> 2) + 32];
;                 }
;             }
;             float mxa = MX3(s0[0], s0[1], s1[0]), mxb = MX3(s0[2], s0[3], s1[1]); mxa = MX3(mxa, s1[2], s1[3]);
; #pragma unroll
;             for (int r = 4; r < 16; r += 4) { mxa = MX3(mxa, s0[r], s0[r + 1]); mxb = MX3(mxb, s0[r + 2], s0[r + 3]); mxa = MX3(mxa, s1[r], s1[r + 1]); mxb = MX3(mxb, s1[r + 2], s1[r + 3]); }
;             float mx = swap_max(__builtin_fmaxf(mxa, mxb));
;             const bool first = (t == 0);
;             if (first || __builtin_amdgcn_ballot_w64(mx > 8.0f) != 0ull) {
;                 const float dl = first ? mx : __builtin_fmaxf(mx, 0.f);
;                 const float f = first ? 1.0f : ex2(-dl);
;                 l *= f; nm -= dl;
; #pragma unroll
;                 for (int i = 0; i < 16; ++i) { o[0][i] *= f; o[1][i] *= f; o[2][i] *= f; o[3][i] *= f; cinit[i] = nm; s0[i] -= dl; s1[i] -= dl; }
;             }
;             asm volatile("s_waitcnt vmcnt(0)" ::: "memory");
;             if (t + 2 < NT) GLOAD(t + 2, sn2);
.LBB0_352:
	s_andn2_b64 vcc, exec, s[50:51]
	s_cbranch_vccnz .LBB0_360
	s_add_i32 s50, s84, 0
	ds_read_b128 v[242:245], v221 offset:4096
	ds_read_b128 v[246:249], v221 offset:4608
	ds_read_b128 v[250:253], v221 offset:6144
	ds_read_b128 v[128:131], v221 offset:6656
	v_add3_u32 v220, s50, v171, v202
	v_add_u32_e32 v220, v220, v203
	s_cmp_ge_u32 s7, s77
	s_cbranch_scc1 .Lpg_u1
	s_add_i32 s92, s82, s93
	s_mov_b32 m0, s92
	s_nop 0
	global_load_lds_dwordx4 v[200:201], off
	global_load_lds_dwordx4 v[200:201], off offset:1024
	global_load_lds_dwordx4 v[200:201], off offset:2048
	global_load_lds_dwordx4 v[200:201], off offset:3072
.Lpg_u1:
	ds_read_b64_tr_b16 v[140:141], v220 offset:16384
	ds_read_b64_tr_b16 v[142:143], v220 offset:16896
	ds_read_b64_tr_b16 v[136:137], v220 offset:20480
	ds_read_b64_tr_b16 v[138:139], v220 offset:20992
	ds_read_b64_tr_b16 v[132:133], v220 offset:24576
	ds_read_b64_tr_b16 v[134:135], v220 offset:25088
	s_waitcnt lgkmcnt(13)
	v_mfma_f32_32x32x16_bf16 v[96:111], v[222:225], v[112:115], v[64:79]
	s_waitcnt lgkmcnt(12)
	v_mfma_f32_32x32x16_bf16 v[80:95], v[226:229], v[112:115], v[64:79]
	s_waitcnt lgkmcnt(11)
	v_mfma_f32_32x32x16_bf16 v[96:111], v[230:233], v[116:119], v[96:111]
	s_waitcnt lgkmcnt(10)
	v_mfma_f32_32x32x16_bf16 v[80:95], v[234:237], v[116:119], v[80:95]
	s_waitcnt lgkmcnt(9)
	v_mfma_f32_32x32x16_bf16 v[96:111], v[242:245], v[120:123], v[96:111]
	s_waitcnt lgkmcnt(8)
	v_mfma_f32_32x32x16_bf16 v[80:95], v[246:249], v[120:123], v[80:95]
	s_waitcnt lgkmcnt(7)
	v_mfma_f32_32x32x16_bf16 v[96:111], v[250:253], v[124:127], v[96:111]
	s_waitcnt lgkmcnt(6)
	v_mfma_f32_32x32x16_bf16 v[80:95], v[128:131], v[124:127], v[80:95]
	ds_read_b64_tr_b16 v[128:129], v220 offset:28672
	ds_read_b64_tr_b16 v[130:131], v220 offset:29184
	s_cmp_lt_u32 s7, s79
	s_cbranch_scc1 .LBB0_355
	v_add_u32_e32 v221, s83, v219
	v_add_u32_e32 v222, 0x18600, v221
	v_add_u32_e32 v224, 0x18680, v221
	v_add_u32_e32 v226, 0x18608, v221
	v_add_u32_e32 v228, 0x18688, v221
	v_add_u32_e32 v230, 0x18620, v221
	v_add_u32_e32 v232, 0x186a0, v221
	v_add_u32_e32 v234, 0x18628, v221
	v_add_u32_e32 v236, 0x186a8, v221
	v_add_u32_e32 v238, 0x18640, v221
	v_add_u32_e32 v240, 0x186c0, v221
	v_add_u32_e32 v242, 0x18648, v221
	v_add_u32_e32 v244, 0x186c8, v221
	v_add_u32_e32 v248, 0x18660, v221
	v_add_u32_e32 v250, 0x186e0, v221
	v_add_u32_e32 v246, 0x18668, v221
	ds_read2_b32 v[222:223], v222 offset1:1
	ds_read2_b32 v[224:225], v224 offset1:1
	ds_read2_b32 v[226:227], v226 offset1:1
	ds_read2_b32 v[228:229], v228 offset1:1
	ds_read2_b32 v[230:231], v230 offset1:1
	ds_read2_b32 v[232:233], v232 offset1:1
	ds_read2_b32 v[234:235], v234 offset1:1
	ds_read2_b32 v[236:237], v236 offset1:1
	ds_read2_b32 v[238:239], v238 offset1:1
	ds_read2_b32 v[240:241], v240 offset1:1
	ds_read2_b32 v[242:243], v242 offset1:1
	ds_read2_b32 v[244:245], v244 offset1:1
	ds_read2_b32 v[246:247], v246 offset1:1
	ds_read2_b32 v[248:249], v248 offset1:1
	v_add_u32_e32 v221, 0x186e8, v221
	ds_read2_b32 v[250:251], v250 offset1:1
	ds_read2_b32 v[252:253], v221 offset1:1
	s_waitcnt lgkmcnt(5)
	v_pk_add_f32 v[106:107], v[106:107], v[242:243]
	s_waitcnt lgkmcnt(3)
	v_pk_add_f32 v[110:111], v[110:111], v[246:247]
	s_waitcnt lgkmcnt(2)
	v_pk_add_f32 v[108:109], v[108:109], v[248:249]
	v_pk_add_f32 v[104:105], v[104:105], v[238:239]
	v_pk_add_f32 v[102:103], v[102:103], v[234:235]
	v_pk_add_f32 v[100:101], v[100:101], v[230:231]
	v_pk_add_f32 v[98:99], v[98:99], v[226:227]
	v_pk_add_f32 v[96:97], v[96:97], v[222:223]
	s_waitcnt lgkmcnt(0)
	v_pk_add_f32 v[94:95], v[94:95], v[252:253]
	v_pk_add_f32 v[92:93], v[92:93], v[250:251]
	v_pk_add_f32 v[90:91], v[90:91], v[244:245]
	v_pk_add_f32 v[88:89], v[88:89], v[240:241]
	v_pk_add_f32 v[86:87], v[86:87], v[236:237]
	v_pk_add_f32 v[84:85], v[84:85], v[232:233]
	v_pk_add_f32 v[82:83], v[82:83], v[228:229]
	v_pk_add_f32 v[80:81], v[80:81], v[224:225]
.LBB0_355:
	s_nop 5
	v_max_f32_e32 v221, v96, v97
	s_nop 0
	v_max3_f32 v222, v98, v99, v81
	v_max3_f32 v221, v221, v80, v82
	v_max3_f32 v221, v221, v83, v100
	v_max3_f32 v222, v222, v102, v103
	v_max3_f32 v221, v221, v101, v84
	v_max3_f32 v222, v222, v86, v87
	v_max3_f32 v221, v221, v85, v104
	v_max3_f32 v222, v222, v106, v107
	v_max3_f32 v221, v221, v105, v88
	v_max3_f32 v222, v222, v90, v91
	v_max3_f32 v221, v221, v89, v108
	v_max3_f32 v222, v222, v110, v111
	v_max3_f32 v221, v221, v109, v92
	v_max3_f32 v222, v222, v94, v95
	v_max3_f32 v221, v221, v93, v222
	v_mov_b32_e32 v222, v221
	s_nop 1
	v_permlane32_swap_b32_e32 v221, v222
	v_max_f32_e32 v221, v221, v222
	v_cmp_lt_f32_e32 vcc, s41, v221
	s_cbranch_vccz .LBB0_357
; DI float ex2(float x) { return __builtin_amdgcn_exp2f(x); }
; DI void attn_unit(const Params& p, int bh, int qb, char* lds, float lam, int tid, int lane, int wid, const bool build_tab) {
;     ...
;             if (first || __builtin_amdgcn_ballot_w64(mx > 8.0f) != 0ull) {
;                 const float dl = first ? mx : __builtin_fmaxf(mx, 0.f);
;                 const float f = first ? 1.0f : ex2(-dl);
;                 l *= f; nm -= dl;
; #pragma unroll
;                 for (int i = 0; i < 16; ++i) { o[0][i] *= f; o[1][i] *= f; o[2][i] *= f; o[3][i] *= f; cinit[i] = nm; s0[i] -= dl; s1[i] -= dl; }
;             }
	v_max_f32_e32 v65, v221, v221
	v_max_f32_e32 v65, 0, v65
	v_exp_f32_e64 v66, -v65
	v_sub_f32_e32 v64, v64, v65
	v_sub_f32_e32 v111, v111, v65
	v_sub_f32_e32 v110, v110, v65
	v_pk_mul_f32 v[62:63], v[62:63], v[66:67] op_sel_hi:[1,0]
	v_pk_mul_f32 v[60:61], v[60:61], v[66:67] op_sel_hi:[1,0]
	v_pk_mul_f32 v[58:59], v[58:59], v[66:67] op_sel_hi:[1,0]
	v_pk_mul_f32 v[56:57], v[56:57], v[66:67] op_sel_hi:[1,0]
	v_pk_mul_f32 v[54:55], v[54:55], v[66:67] op_sel_hi:[1,0]
	v_pk_mul_f32 v[52:53], v[52:53], v[66:67] op_sel_hi:[1,0]
	v_pk_mul_f32 v[50:51], v[50:51], v[66:67] op_sel_hi:[1,0]
	v_pk_mul_f32 v[48:49], v[48:49], v[66:67] op_sel_hi:[1,0]
	v_pk_mul_f32 v[46:47], v[46:47], v[66:67] op_sel_hi:[1,0]
	v_pk_mul_f32 v[44:45], v[44:45], v[66:67] op_sel_hi:[1,0]
	v_pk_mul_f32 v[42:43], v[42:43], v[66:67] op_sel_hi:[1,0]
	v_pk_mul_f32 v[40:41], v[40:41], v[66:67] op_sel_hi:[1,0]
	v_pk_mul_f32 v[38:39], v[38:39], v[66:67] op_sel_hi:[1,0]
	v_pk_mul_f32 v[36:37], v[36:37], v[66:67] op_sel_hi:[1,0]
	v_pk_mul_f32 v[34:35], v[34:35], v[66:67] op_sel_hi:[1,0]
	v_pk_mul_f32 v[32:33], v[32:33], v[66:67] op_sel_hi:[1,0]
	v_pk_mul_f32 v[30:31], v[30:31], v[66:67] op_sel_hi:[1,0]
	v_pk_mul_f32 v[28:29], v[28:29], v[66:67] op_sel_hi:[1,0]
	v_pk_mul_f32 v[26:27], v[26:27], v[66:67] op_sel_hi:[1,0]
	v_pk_mul_f32 v[24:25], v[24:25], v[66:67] op_sel_hi:[1,0]
	v_pk_mul_f32 v[22:23], v[22:23], v[66:67] op_sel_hi:[1,0]
	v_pk_mul_f32 v[20:21], v[20:21], v[66:67] op_sel_hi:[1,0]
	v_pk_mul_f32 v[18:19], v[18:19], v[66:67] op_sel_hi:[1,0]
	v_pk_mul_f32 v[16:17], v[16:17], v[66:67] op_sel_hi:[1,0]
	v_pk_mul_f32 v[14:15], v[14:15], v[66:67] op_sel_hi:[1,0]
	v_pk_mul_f32 v[12:13], v[12:13], v[66:67] op_sel_hi:[1,0]
	v_pk_mul_f32 v[10:11], v[10:11], v[66:67] op_sel_hi:[1,0]
	v_pk_mul_f32 v[8:9], v[8:9], v[66:67] op_sel_hi:[1,0]
	v_pk_mul_f32 v[6:7], v[6:7], v[66:67] op_sel_hi:[1,0]
	v_pk_mul_f32 v[4:5], v[4:5], v[66:67] op_sel_hi:[1,0]
	v_pk_mul_f32 v[2:3], v[2:3], v[66:67] op_sel_hi:[1,0]
	v_pk_mul_f32 v[0:1], v[0:1], v[66:67] op_sel_hi:[1,0]
	v_sub_f32_e32 v109, v109, v65
	v_sub_f32_e32 v108, v108, v65
	v_sub_f32_e32 v107, v107, v65
	v_sub_f32_e32 v106, v106, v65
	v_sub_f32_e32 v105, v105, v65
	v_sub_f32_e32 v104, v104, v65
	v_sub_f32_e32 v103, v103, v65
	v_sub_f32_e32 v102, v102, v65
	v_sub_f32_e32 v101, v101, v65
	v_sub_f32_e32 v100, v100, v65
	v_sub_f32_e32 v99, v99, v65
	v_sub_f32_e32 v98, v98, v65
	v_sub_f32_e32 v97, v97, v65
	v_sub_f32_e32 v96, v96, v65
	v_sub_f32_e32 v95, v95, v65
	v_sub_f32_e32 v94, v94, v65
	v_sub_f32_e32 v93, v93, v65
	v_sub_f32_e32 v92, v92, v65
	v_sub_f32_e32 v91, v91, v65
	v_sub_f32_e32 v90, v90, v65
	v_sub_f32_e32 v89, v89, v65
	v_sub_f32_e32 v88, v88, v65
	v_sub_f32_e32 v87, v87, v65
	v_sub_f32_e32 v86, v86, v65
	v_sub_f32_e32 v85, v85, v65
	v_sub_f32_e32 v84, v84, v65
	v_sub_f32_e32 v83, v83, v65
	v_sub_f32_e32 v82, v82, v65
	v_sub_f32_e32 v81, v81, v65
	v_sub_f32_e32 v80, v80, v65
	v_mul_f32_e32 v146, v146, v66
	v_mov_b32_e32 v65, v64
	v_mov_b32_e32 v66, v64
	v_mov_b32_e32 v67, v64
	v_mov_b32_e32 v68, v64
	v_mov_b32_e32 v69, v64
	v_mov_b32_e32 v70, v64
	v_mov_b32_e32 v71, v64
	v_mov_b32_e32 v72, v64
	v_mov_b32_e32 v73, v64
	v_mov_b32_e32 v74, v64
	v_mov_b32_e32 v75, v64
	v_mov_b32_e32 v76, v64
	v_mov_b32_e32 v77, v64
	v_mov_b32_e32 v78, v64
	v_mov_b32_e32 v79, v64
; #define GLOAD(t_, slotoff_) do { const char* kb_ = KGc + ((size_t)(t_) << 14); const char* vb_ = VGc + ((size_t)(t_) << 14); \
;         const unsigned d_ = (unsigned)__builtin_amdgcn_readfirstlane((int)(ldsbase + (slotoff_) + wid * 1024)); \
;         GLDS16(kb_, d_); GLDS16(kb_ + 8192, d_ + 8192u); GLDS16(vb_, d_ + 16384u); GLDS16(vb_ + 8192, d_ + 24576u); } while (0)
; #define SCHEDB() __builtin_amdgcn_sched_barrier(0)
; #define LOADV(dst, ks_) do { _Pragma("unroll") for (int dvb = 0; dvb < 4; ++dvb) { dst[2 * dvb] = vtr(vp + dvb * 4096 + (ks_) * 1024); dst[2 * dvb + 1] = vtr(vp + dvb * 4096 + (ks_) * 1024 + 512); } } while (0)
; #define MF4(src, pfrag) do { _Pragma("unroll") for (int dvb = 0; dvb < 4; ++dvb) { \
;         const bf16x8 vf_ = __builtin_shufflevector(src[2 * dvb], src[2 * dvb + 1], 0, 1, 2, 3, 4, 5, 6, 7); o[dvb] = MFMA32(vf_, pfrag, o[dvb]); } } while (0)
; #define EXPQ(S, lo_, RS, PF) do { _Pragma("unroll") for (int i = lo_; i < lo_ + 8; ++i) { S[i] = ex2(S[i]); RS += S[i]; } \
;               u32x4 w_; w_.x = pk2(S[lo_], S[lo_ + 1]); w_.y = pk2(S[lo_ + 2], S[lo_ + 3]); w_.z = pk2(S[lo_ + 4], S[lo_ + 5]); w_.w = pk2(S[lo_ + 6], S[lo_ + 7]); PF = __builtin_bit_cast(bf16x8, w_); } while (0)
; DI void attn_unit(const Params& p, int bh, int qb, char* lds, float lam, int tid, int lane, int wid, const bool build_tab) {
;     ...
;             EXPQ(s0, 0, rs0, pf[0]);
;             LOADV(vb, 1);
;             MF4(va, pf[0]);
;             EXPQ(s0, 8, rs1, pf[1]);
;             LOADV(va, 2);
;             MF4(vb, pf[1]);
;             EXPQ(s1, 0, rs0, pf[2]);
;             LOADV(vb, 3);
;             MF4(va, pf[2]);
;             EXPQ(s1, 8, rs1, pf[3]);
;             MF4(vb, pf[3]);
;             l += rs0 + rs1;
;     ...
;         } else {
;             asm volatile("s_waitcnt vmcnt(0)" ::: "memory");
;             if (t + 2 < NT) GLOAD(t + 2, sn2);
;         }
;         SCHEDB();
;         __builtin_amdgcn_s_barrier();
;         SCHEDB();
;         { const int tmp = sc; sc = sn1; sn1 = sn2; sn2 = tmp; }
.LBB0_357:
.LBB0_359:
	ds_read_b64_tr_b16 v[242:243], v220 offset:21504
	ds_read_b64_tr_b16 v[244:245], v220 offset:22016
	ds_read_b64_tr_b16 v[246:247], v220 offset:25600
	ds_read_b64_tr_b16 v[248:249], v220 offset:26112
	v_exp_f32_e32 v222, v96
	v_exp_f32_e32 v224, v97
	v_exp_f32_e32 v226, v98
	v_exp_f32_e32 v228, v99
	v_exp_f32_e32 v230, v100
	v_exp_f32_e32 v232, v101
	v_exp_f32_e32 v234, v102
	v_exp_f32_e32 v236, v103
	v_cvt_pk_bf16_f32 v96, v222, v224
	v_cvt_pk_bf16_f32 v97, v226, v228
	v_cvt_pk_bf16_f32 v98, v230, v232
	v_cvt_pk_bf16_f32 v99, v234, v236
	ds_read_b64_tr_b16 v[100:101], v220 offset:17408
	ds_read_b64_tr_b16 v[102:103], v220 offset:17920
	s_waitcnt lgkmcnt(12)
	v_mfma_f32_32x32x16_bf16 v[48:63], v[140:143], v[96:99], v[48:63]
	ds_read_b64_tr_b16 v[250:251], v220 offset:29696
	ds_read_b64_tr_b16 v[252:253], v220 offset:30208
	v_exp_f32_e32 v223, v104
	v_exp_f32_e32 v225, v105
	v_exp_f32_e32 v227, v106
	v_add_f32_e32 v221, v224, v222
	s_waitcnt lgkmcnt(12)
	v_mfma_f32_32x32x16_bf16 v[32:47], v[136:139], v[96:99], v[32:47]
	v_exp_f32_e32 v229, v107
	v_exp_f32_e32 v231, v108
	v_exp_f32_e32 v233, v109
	v_add_f32_e32 v221, v226, v221
	s_waitcnt lgkmcnt(10)
	v_mfma_f32_32x32x16_bf16 v[16:31], v[132:135], v[96:99], v[16:31]
	v_exp_f32_e32 v235, v110
	v_exp_f32_e32 v237, v111
	v_add_f32_e32 v221, v228, v221
	v_add_f32_e32 v221, v230, v221
	ds_read_b64_tr_b16 v[104:105], v220 offset:18432
	ds_read_b64_tr_b16 v[106:107], v220 offset:18944
	ds_read_b64_tr_b16 v[108:109], v220 offset:19456
	ds_read_b64_tr_b16 v[110:111], v220 offset:19968
	s_waitcnt lgkmcnt(12)
	v_mfma_f32_32x32x16_bf16 v[0:15], v[128:131], v[96:99], v[0:15]
	ds_read_b64_tr_b16 v[128:129], v220 offset:26624
	ds_read_b64_tr_b16 v[130:131], v220 offset:27136
	v_cvt_pk_bf16_f32 v96, v223, v225
	v_cvt_pk_bf16_f32 v97, v227, v229
	v_cvt_pk_bf16_f32 v98, v231, v233
	v_cvt_pk_bf16_f32 v99, v235, v237
	v_exp_f32_e32 v140, v84
	v_exp_f32_e32 v142, v85
	s_waitcnt lgkmcnt(8)
	v_mfma_f32_32x32x16_bf16 v[48:63], v[100:103], v[96:99], v[48:63]
	v_exp_f32_e32 v238, v86
	v_exp_f32_e32 v240, v87
	v_add_f32_e32 v221, v232, v221
	ds_read_b64_tr_b16 v[84:85], v220 offset:22528
	ds_read_b64_tr_b16 v[86:87], v220 offset:23040
	v_exp_f32_e32 v136, v82
	s_waitcnt lgkmcnt(14)
	v_mfma_f32_32x32x16_bf16 v[32:47], v[242:245], v[96:99], v[32:47]
	ds_read_b64_tr_b16 v[242:243], v220 offset:23552
	ds_read_b64_tr_b16 v[244:245], v220 offset:24064
	v_exp_f32_e32 v138, v83
	v_exp_f32_e32 v132, v80
	v_exp_f32_e32 v134, v81
	v_add_f32_e32 v221, v234, v221
	s_waitcnt lgkmcnt(14)
	v_mfma_f32_32x32x16_bf16 v[16:31], v[246:249], v[96:99], v[16:31]
	ds_read_b64_tr_b16 v[246:247], v220 offset:27648
	ds_read_b64_tr_b16 v[248:249], v220 offset:28160
	v_cvt_pk_bf16_f32 v80, v132, v134
	v_cvt_pk_bf16_f32 v81, v136, v138
	v_cvt_pk_bf16_f32 v82, v140, v142
	v_cvt_pk_bf16_f32 v83, v238, v240
	v_exp_f32_e32 v133, v88
	v_exp_f32_e32 v135, v89
	s_waitcnt lgkmcnt(12)
	v_mfma_f32_32x32x16_bf16 v[0:15], v[250:253], v[96:99], v[0:15]
	ds_read_b64_tr_b16 v[250:251], v220 offset:31744
	ds_read_b64_tr_b16 v[252:253], v220 offset:32256
	v_exp_f32_e32 v137, v90
	v_exp_f32_e32 v139, v91
	v_add_f32_e32 v221, v236, v221
	ds_read_b64_tr_b16 v[88:89], v220 offset:30720
	ds_read_b64_tr_b16 v[90:91], v220 offset:31232
	v_exp_f32_e32 v141, v92
	s_waitcnt lgkmcnt(14)
	v_mfma_f32_32x32x16_bf16 v[48:63], v[104:107], v[80:83], v[48:63]
	v_exp_f32_e32 v143, v93
	v_exp_f32_e32 v239, v94
	v_exp_f32_e32 v241, v95
	v_add_f32_e32 v221, v132, v221
	s_waitcnt lgkmcnt(8)
	v_mfma_f32_32x32x16_bf16 v[32:47], v[84:87], v[80:83], v[32:47]
	v_add_f32_e32 v93, v225, v223
	v_add_f32_e32 v221, v134, v221
	v_add_f32_e32 v93, v227, v93
	v_add_f32_e32 v221, v136, v221
	v_add_f32_e32 v93, v229, v93
	v_add_f32_e32 v221, v138, v221
	s_waitcnt lgkmcnt(10)
	v_mfma_f32_32x32x16_bf16 v[16:31], v[128:131], v[80:83], v[16:31]
	v_add_f32_e32 v93, v231, v93
	v_add_f32_e32 v221, v140, v221
	v_add_f32_e32 v93, v233, v93
	v_add_f32_e32 v221, v142, v221
	v_add_f32_e32 v93, v235, v93
	v_add_f32_e32 v221, v238, v221
	v_add_f32_e32 v93, v237, v93
	s_waitcnt lgkmcnt(0)
	v_mfma_f32_32x32x16_bf16 v[0:15], v[88:91], v[80:83], v[0:15]
	v_cvt_pk_bf16_f32 v80, v133, v135
	v_cvt_pk_bf16_f32 v81, v137, v139
	v_cvt_pk_bf16_f32 v82, v141, v143
	v_cvt_pk_bf16_f32 v83, v239, v241
	v_add_f32_e32 v221, v240, v221
	v_add_f32_e32 v93, v133, v93
	s_waitcnt lgkmcnt(12)
	v_mfma_f32_32x32x16_bf16 v[48:63], v[108:111], v[80:83], v[48:63]
	v_add_f32_e32 v93, v135, v93
	v_add_f32_e32 v93, v137, v93
	s_waitcnt lgkmcnt(6)
	v_mfma_f32_32x32x16_bf16 v[32:47], v[242:245], v[80:83], v[32:47]
	v_add_f32_e32 v93, v139, v93
	v_add_f32_e32 v93, v141, v93
	s_waitcnt lgkmcnt(4)
	v_mfma_f32_32x32x16_bf16 v[16:31], v[246:249], v[80:83], v[16:31]
	v_add_f32_e32 v93, v143, v93
	v_add_f32_e32 v93, v239, v93
	s_waitcnt lgkmcnt(2)
	v_mfma_f32_32x32x16_bf16 v[0:15], v[250:253], v[80:83], v[0:15]
	v_add_f32_e32 v93, v241, v93
	v_add_f32_e32 v221, v221, v93
	v_add_f32_e32 v146, v146, v221
	s_add_i32 s96, s80, s61
	v_add3_u32 v221, s96, v204, v205
	ds_read_b128 v[222:225], v221
	ds_read_b128 v[226:229], v221 offset:512
	ds_read_b128 v[230:233], v221 offset:2048
	ds_read_b128 v[234:237], v221 offset:2560
	s_waitcnt vmcnt(0)

; DI float ex2(float x) { return __builtin_amdgcn_exp2f(x); }
; DI float swap_max(float m) { auto rr = __builtin_amdgcn_permlane32_swap(__float_as_uint(m), __float_as_uint(m), false, false); return __builtin_fmaxf(__uint_as_float(rr[0]), __uint_as_float(rr[1])); }
; #define GLOAD(t_, slotoff_) do { const char* kb_ = KGc + ((size_t)(t_) << 14); const char* vb_ = VGc + ((size_t)(t_) << 14); \
;         const unsigned d_ = (unsigned)__builtin_amdgcn_readfirstlane((int)(ldsbase + (slotoff_) + wid * 1024)); \
;         GLDS16(kb_, d_); GLDS16(kb_ + 8192, d_ + 8192u); GLDS16(vb_, d_ + 16384u); GLDS16(vb_ + 8192, d_ + 24576u); } while (0)
; #define SCHEDB() __builtin_amdgcn_sched_barrier(0)
; #define LOADV(dst, ks_) do { _Pragma("unroll") for (int dvb = 0; dvb < 4; ++dvb) { dst[2 * dvb] = vtr(vp + dvb * 4096 + (ks_) * 1024); dst[2 * dvb + 1] = vtr(vp + dvb * 4096 + (ks_) * 1024 + 512); } } while (0)
; DI void attn_unit(const Params& p, int bh, int qb, char* lds, float lam, int tid, int lane, int wid, const bool build_tab) {
;     ...
;             float mx = swap_max(__builtin_fmaxf(mxa, mxb));
;             const bool first = (t == 0);
;             if (first || __builtin_amdgcn_ballot_w64(mx > 8.0f) != 0ull) {
;                 const float dl = first ? mx : __builtin_fmaxf(mx, 0.f);
;                 const float f = first ? 1.0f : ex2(-dl);
;                 l *= f; nm -= dl;
; #pragma unroll
;                 for (int i = 0; i < 16; ++i) { o[0][i] *= f; o[1][i] *= f; o[2][i] *= f; o[3][i] *= f; cinit[i] = nm; s0[i] -= dl; s1[i] -= dl; }
;             }
;             asm volatile("s_waitcnt vmcnt(0)" ::: "memory");
;             if (t + 2 < NT) GLOAD(t + 2, sn2);
;             float rs0 = 0.f, rs1 = 0.f;
;     ...
;             EXPQ(s0, 0, rs0, pf[0]);
;             LOADV(vb, 1);
;             MF4(va, pf[0]);
;             EXPQ(s0, 8, rs1, pf[1]);
;             LOADV(va, 2);
;             MF4(vb, pf[1]);
;             EXPQ(s1, 0, rs0, pf[2]);
;             LOADV(vb, 3);
;             MF4(va, pf[2]);
;             EXPQ(s1, 8, rs1, pf[3]);
;             MF4(vb, pf[3]);
;             l += rs0 + rs1;
;     ...
;         } else {
;             asm volatile("s_waitcnt vmcnt(0)" ::: "memory");
;             if (t + 2 < NT) GLOAD(t + 2, sn2);
;         }
;         SCHEDB();
;         __builtin_amdgcn_s_barrier();
;         SCHEDB();
;         { const int tmp = sc; sc = sn1; sn1 = sn2; sn2 = tmp; }
.LBB0_370:
	v_max_f32_e32 v29, v29, v29
	v_max_f32_e32 v28, v28, v28
	v_max_f32_e32 v146, v28, v29
	v_sub_f32_e32 v0, v0, v146
	v_sub_f32_e32 v1, v1, v146
	v_sub_f32_e32 v2, v2, v146
	v_sub_f32_e32 v3, v3, v146
	v_sub_f32_e32 v4, v4, v146
	v_sub_f32_e32 v5, v5, v146
	v_sub_f32_e32 v6, v6, v146
	v_sub_f32_e32 v7, v7, v146
	v_exp_f32_e32 v110, v0
	v_exp_f32_e32 v128, v1
	v_exp_f32_e32 v130, v2
	v_exp_f32_e32 v132, v3
	v_exp_f32_e32 v90, v4
	v_exp_f32_e32 v88, v5
	v_exp_f32_e32 v86, v6
	v_exp_f32_e32 v84, v7
	v_cvt_pk_bf16_f32 v0, v110, v128
	v_cvt_pk_bf16_f32 v1, v130, v132
	v_cvt_pk_bf16_f32 v2, v90, v88
	v_cvt_pk_bf16_f32 v3, v86, v84
	v_sub_f32_e32 v85, v8, v146
	v_sub_f32_e32 v87, v9, v146
	s_waitcnt lgkmcnt(6)
	v_mfma_f32_32x32x16_bf16 v[48:63], v[24:27], v[0:3], 0
	v_sub_f32_e32 v89, v10, v146
	v_sub_f32_e32 v91, v11, v146
	v_sub_f32_e32 v96, v12, v146
	v_sub_f32_e32 v97, v13, v146
	v_sub_f32_e32 v98, v14, v146
	v_sub_f32_e32 v99, v15, v146
	ds_read_b64_tr_b16 v[92:93], v217 offset:17408
	ds_read_b64_tr_b16 v[94:95], v217 offset:17920
	v_exp_f32_e32 v111, v85
	v_exp_f32_e32 v129, v87
	v_exp_f32_e32 v131, v89
	v_exp_f32_e32 v133, v91
	v_exp_f32_e32 v91, v96
	v_exp_f32_e32 v89, v97
	v_exp_f32_e32 v87, v98
	v_exp_f32_e32 v85, v99
	s_waitcnt lgkmcnt(6)
	v_mfma_f32_32x32x16_bf16 v[32:47], v[20:23], v[0:3], 0
	ds_read_b64_tr_b16 v[96:97], v217 offset:18432
	ds_read_b64_tr_b16 v[98:99], v217 offset:18944
	v_sub_f32_e32 v64, v64, v146
	v_sub_f32_e32 v65, v65, v146
	v_sub_f32_e32 v66, v66, v146
	v_sub_f32_e32 v67, v67, v146
	v_sub_f32_e32 v70, v70, v146
	v_sub_f32_e32 v71, v71, v146
	s_waitcnt lgkmcnt(6)
	v_mfma_f32_32x32x16_bf16 v[16:31], v[16:19], v[0:3], 0
	v_exp_f32_e32 v134, v66
	v_exp_f32_e32 v136, v67
	v_exp_f32_e32 v142, v70
	v_exp_f32_e32 v176, v71
	v_sub_f32_e32 v78, v78, v146
	v_sub_f32_e32 v79, v79, v146
	v_exp_f32_e32 v143, v78
	s_waitcnt lgkmcnt(4)
	v_mfma_f32_32x32x16_bf16 v[0:15], v[80:83], v[0:3], 0
	v_cvt_pk_bf16_f32 v80, v111, v129
	v_cvt_pk_bf16_f32 v81, v131, v133
	v_cvt_pk_bf16_f32 v82, v91, v89
	v_cvt_pk_bf16_f32 v83, v87, v85
	v_cvt_pk_bf16_f32 v67, v142, v176
	v_exp_f32_e32 v177, v79
	s_and_b32 s52, s54, 63
	s_waitcnt lgkmcnt(2)
	v_mfma_f32_32x32x16_bf16 v[48:63], v[92:95], v[80:83], v[48:63]
	ds_read_b64_tr_b16 v[92:93], v217 offset:21504
	ds_read_b64_tr_b16 v[94:95], v217 offset:22016
	ds_read_b64_tr_b16 v[100:101], v217 offset:19968
	s_lshl_b32 s53, s52, 7
	s_lshl_b32 s55, s67, 1
	s_add_i32 s56, s35, s55
	s_mov_b32 s51, 1
	s_add_i32 s56, s56, 1
	s_add_i32 s57, s55, -2
	s_waitcnt lgkmcnt(1)
	v_mfma_f32_32x32x16_bf16 v[32:47], v[92:95], v[80:83], v[32:47]
	ds_read_b64_tr_b16 v[92:93], v217 offset:25600
	ds_read_b64_tr_b16 v[94:95], v217 offset:26112
	ds_read_b64_tr_b16 v[102:103], v217 offset:29696
	ds_read_b64_tr_b16 v[104:105], v217 offset:30208
	ds_read_b64_tr_b16 v[106:107], v217 offset:26624
	ds_read_b64_tr_b16 v[108:109], v217 offset:27136
	s_lshl_b32 s54, s52, 9
	s_waitcnt lgkmcnt(4)
	v_mfma_f32_32x32x16_bf16 v[16:31], v[92:95], v[80:83], v[16:31]
	v_sub_f32_e32 v92, v68, v146
	v_sub_f32_e32 v93, v69, v146
	v_exp_f32_e32 v138, v92
	v_exp_f32_e32 v140, v93
	ds_read_b64_tr_b16 v[68:69], v217 offset:28160
	v_cvt_pk_bf16_f32 v66, v138, v140
	s_waitcnt lgkmcnt(3)
	v_mfma_f32_32x32x16_bf16 v[0:15], v[102:105], v[80:83], v[0:15]
	v_exp_f32_e32 v102, v64
	v_exp_f32_e32 v104, v65
	ds_read_b64_tr_b16 v[80:81], v217 offset:22528
	ds_read_b64_tr_b16 v[82:83], v217 offset:23040
	ds_read_b64_tr_b16 v[92:93], v217 offset:23552
	ds_read_b64_tr_b16 v[94:95], v217 offset:24064
	v_cvt_pk_bf16_f32 v65, v134, v136
	v_cvt_pk_bf16_f32 v64, v102, v104
	s_nop 1
	v_mfma_f32_32x32x16_bf16 v[48:63], v[96:99], v[64:67], v[48:63]
	ds_read_b64_tr_b16 v[98:99], v217 offset:19456
	v_sub_f32_e32 v96, v76, v146
	v_sub_f32_e32 v97, v77, v146
	v_exp_f32_e32 v139, v96
	v_exp_f32_e32 v141, v97
	s_waitcnt lgkmcnt(3)
	v_mfma_f32_32x32x16_bf16 v[32:47], v[80:83], v[64:67], v[32:47]
	v_sub_f32_e32 v80, v72, v146
	v_sub_f32_e32 v81, v73, v146
	ds_read_b64_tr_b16 v[70:71], v217 offset:30720
	ds_read_b64_tr_b16 v[72:73], v217 offset:31232
	v_sub_f32_e32 v82, v74, v146
	v_sub_f32_e32 v83, v75, v146
	ds_read_b64_tr_b16 v[74:75], v217 offset:31744
	ds_read_b64_tr_b16 v[76:77], v217 offset:32256
	v_exp_f32_e32 v103, v80
	v_mfma_f32_32x32x16_bf16 v[16:31], v[106:109], v[64:67], v[16:31]
	v_exp_f32_e32 v105, v81
	v_exp_f32_e32 v135, v82
	v_exp_f32_e32 v137, v83
	s_waitcnt lgkmcnt(2)
	v_mfma_f32_32x32x16_bf16 v[0:15], v[70:73], v[64:67], v[0:15]
	ds_read_b64_tr_b16 v[66:67], v217 offset:27648
	v_cvt_pk_bf16_f32 v70, v103, v105
	v_cvt_pk_bf16_f32 v71, v135, v137
	v_cvt_pk_bf16_f32 v72, v139, v141
	v_cvt_pk_bf16_f32 v73, v143, v177
	v_add_lshl_u32 v65, v214, s53, 2
	v_sub_f32_e32 v64, 0, v146
	s_waitcnt lgkmcnt(0)
	v_mfma_f32_32x32x16_bf16 v[16:31], v[66:69], v[70:73], v[16:31]
	v_add_f32_e64 v66, v110, 0
	v_add_f32_e64 v67, v111, 0
	v_sub_u32_e32 v146, v213, v65
	v_add_f32_e64 v66, v128, v66
	v_add_f32_e64 v67, v129, v67
	v_pk_add_f32 v[66:67], v[130:131], v[66:67]
	s_nop 0
	v_pk_add_f32 v[66:67], v[132:133], v[66:67]
	v_mfma_f32_32x32x16_bf16 v[48:63], v[98:101], v[70:73], v[48:63]
	v_add_f32_e64 v66, v90, v66
	v_add_f32_e64 v67, v91, v67
	v_add_f32_e64 v66, v88, v66
	v_add_f32_e64 v67, v89, v67
	v_add_f32_e64 v66, v86, v66
	v_add_f32_e64 v67, v87, v67
	v_pk_add_f32 v[66:67], v[84:85], v[66:67]
	v_mfma_f32_32x32x16_bf16 v[32:47], v[92:95], v[70:73], v[32:47]
	v_add_f32_e64 v66, v102, v66
	v_add_f32_e64 v67, v103, v67
	v_add_f32_e64 v66, v104, v66
	v_add_f32_e64 v67, v105, v67
	v_add_f32_e64 v66, v134, v66
	v_add_f32_e64 v67, v135, v67
	v_pk_add_f32 v[66:67], v[136:137], v[66:67]
	v_mfma_f32_32x32x16_bf16 v[0:15], v[74:77], v[70:73], v[0:15]
	v_add_f32_e64 v66, v138, v66
	v_add_f32_e64 v67, v139, v67
	v_add_f32_e64 v66, v140, v66
	v_add_f32_e64 v67, v141, v67
	v_add_f32_e64 v66, v142, v66
	v_add_f32_e64 v67, v143, v67
	v_pk_add_f32 v[66:67], v[176:177], v[66:67]
	s_nop 0
	v_add_f32_e32 v65, v66, v67
	v_add_f32_e32 v176, 0, v65
	s_waitcnt vmcnt(0)
	s_add_i32 s96, s61, 0x8000
	v_add3_u32 v244, s96, v204, v205
	ds_read_b128 v[178:181], v244
	ds_read_b128 v[182:185], v244 offset:512
	ds_read_b128 v[186:189], v244 offset:2048
	ds_read_b128 v[190:193], v244 offset:2560
	s_barrier
	s_mov_b32 s67, 0
	s_mov_b32 s68, 0x10000
	s_mov_b32 s52, 0x8000
	s_movk_i32 s69, 0xff00
	v_mov_b32_e32 v65, v64
	v_mov_b32_e32 v66, v64
	v_mov_b32_e32 v67, v64
	v_mov_b32_e32 v68, v64
	v_mov_b32_e32 v69, v64
	v_mov_b32_e32 v70, v64
	v_mov_b32_e32 v71, v64
	v_mov_b32_e32 v72, v64
	v_mov_b32_e32 v73, v64
	v_mov_b32_e32 v74, v64
	v_mov_b32_e32 v75, v64
	v_mov_b32_e32 v76, v64
	v_mov_b32_e32 v77, v64
	v_mov_b32_e32 v78, v64
	v_mov_b32_e32 v79, v64
	s_mov_b32 s70, s52
	s_cmp_ge_u32 s51, s56
	s_mov_b64 s[52:53], -1
	s_cbranch_scc0 .LBB0_372

; DI float ex2(float x) { return __builtin_amdgcn_exp2f(x); }
; DI float swap_max(float m) { auto rr = __builtin_amdgcn_permlane32_swap(__float_as_uint(m), __float_as_uint(m), false, false); return __builtin_fmaxf(__uint_as_float(rr[0]), __uint_as_float(rr[1])); }
; DI void attn_unit(const Params& p, int bh, int qb, char* lds, float lam, int tid, int lane, int wid, const bool build_tab) {
;     ...
;             const lds_cptr kp = (lds_cptr)lds + sc + map * 8192 + hi * 1024 + r32 * 16;
;             bf16x8 kf[8];
; #pragma unroll
;             for (int d0 = 0; d0 < 4; ++d0) {
;                 kf[2 * d0] = *(const __attribute__((address_space(3))) bf16x8*)(kp + d0 * 2048);
;                 kf[2 * d0 + 1] = *(const __attribute__((address_space(3))) bf16x8*)(kp + d0 * 2048 + 512);
;             }
;             f32x16 s0 = cinit, s1 = cinit;
; #pragma unroll
;             for (int d0 = 0; d0 < 4; ++d0) { s0 = MFMA32(kf[2 * d0], qf[d0], s0); s1 = MFMA32(kf[2 * d0 + 1], qf[d0], s1); }
;             LOADV(va, 0);
;             if (t >= 2 * qb - 2) {
;                 const float* tb = tab + (64 * t - (qrow0 + r32) + 256 + 4 * hi);
; #pragma unroll
;                 for (int i = 0; i < 16; ++i) {
;                     s0[i] += tb[(i & 3) + 8 * (i >> 2)];
;                     s1[i] += tb[(i & 3) + 8 * (i >> 2) + 32];
;                 }
;             }
;             float mxa = MX3(s0[0], s0[1], s1[0]), mxb = MX3(s0[2], s0[3], s1[1]); mxa = MX3(mxa, s1[2], s1[3]);
; #pragma unroll
;             for (int r = 4; r < 16; r += 4) { mxa = MX3(mxa, s0[r], s0[r + 1]); mxb = MX3(mxb, s0[r + 2], s0[r + 3]); mxa = MX3(mxa, s1[r], s1[r + 1]); mxb = MX3(mxb, s1[r + 2], s1[r + 3]); }
;             float mx = swap_max(__builtin_fmaxf(mxa, mxb));
;             const bool first = (t == 0);
;             if (first || __builtin_amdgcn_ballot_w64(mx > 8.0f) != 0ull) {
;                 const float dl = first ? mx : __builtin_fmaxf(mx, 0.f);
;                 const float f = first ? 1.0f : ex2(-dl);
;                 l *= f; nm -= dl;
; #pragma unroll
;                 for (int i = 0; i < 16; ++i) { o[0][i] *= f; o[1][i] *= f; o[2][i] *= f; o[3][i] *= f; cinit[i] = nm; s0[i] -= dl; s1[i] -= dl; }
;             }
;             asm volatile("s_waitcnt vmcnt(0)" ::: "memory");
;             if (t + 2 < NT) GLOAD(t + 2, sn2);
.LBB0_372:
	s_andn2_b64 vcc, exec, s[52:53]
	s_cbranch_vccnz .LBB0_380
	s_add_i32 s52, s70, 0
	ds_read_b128 v[230:233], v244 offset:4096
	ds_read_b128 v[234:237], v244 offset:4608
	ds_read_b128 v[238:241], v244 offset:6144
	ds_read_b128 v[128:131], v244 offset:6656
	v_add3_u32 v177, s52, v171, v202
	v_add_u32_e32 v177, v177, v203
	s_cmp_ge_u32 s51, s55
	s_cbranch_scc1 .Lpg_u2
	s_add_i32 s92, s67, s93
	s_mov_b32 m0, s92
	s_nop 0
	global_load_lds_dwordx4 v[174:175], off
	global_load_lds_dwordx4 v[174:175], off offset:1024
	global_load_lds_dwordx4 v[174:175], off offset:2048
	global_load_lds_dwordx4 v[174:175], off offset:3072
.Lpg_u2:
	ds_read_b64_tr_b16 v[140:141], v177 offset:16384
	ds_read_b64_tr_b16 v[142:143], v177 offset:16896
	ds_read_b64_tr_b16 v[136:137], v177 offset:20480
	ds_read_b64_tr_b16 v[138:139], v177 offset:20992
	ds_read_b64_tr_b16 v[132:133], v177 offset:24576
	ds_read_b64_tr_b16 v[134:135], v177 offset:25088
	s_waitcnt lgkmcnt(13)
	v_mfma_f32_32x32x16_bf16 v[96:111], v[178:181], v[112:115], v[64:79]
	s_waitcnt lgkmcnt(12)
	v_mfma_f32_32x32x16_bf16 v[80:95], v[182:185], v[112:115], v[64:79]
	s_waitcnt lgkmcnt(11)
	v_mfma_f32_32x32x16_bf16 v[96:111], v[186:189], v[116:119], v[96:111]
	s_waitcnt lgkmcnt(10)
	v_mfma_f32_32x32x16_bf16 v[80:95], v[190:193], v[116:119], v[80:95]
	s_waitcnt lgkmcnt(9)
	v_mfma_f32_32x32x16_bf16 v[96:111], v[230:233], v[120:123], v[96:111]
	s_waitcnt lgkmcnt(8)
	v_mfma_f32_32x32x16_bf16 v[80:95], v[234:237], v[120:123], v[80:95]
	s_waitcnt lgkmcnt(7)
	v_mfma_f32_32x32x16_bf16 v[96:111], v[238:241], v[124:127], v[96:111]
	s_waitcnt lgkmcnt(6)
	v_mfma_f32_32x32x16_bf16 v[80:95], v[128:131], v[124:127], v[80:95]
	ds_read_b64_tr_b16 v[128:129], v177 offset:28672
	ds_read_b64_tr_b16 v[130:131], v177 offset:29184
	s_cmp_lt_i32 s51, s57
	s_cbranch_scc1 .LBB0_375
	v_add_u32_e32 v219, s69, v146
	v_add_u32_e32 v178, 0x18600, v219
	v_add_u32_e32 v180, 0x18680, v219
	v_add_u32_e32 v182, 0x18608, v219
	v_add_u32_e32 v184, 0x18688, v219
	v_add_u32_e32 v186, 0x18620, v219
	v_add_u32_e32 v188, 0x186a0, v219
	v_add_u32_e32 v190, 0x18628, v219
	v_add_u32_e32 v192, 0x186a8, v219
	v_add_u32_e32 v194, 0x18640, v219
	v_add_u32_e32 v196, 0x186c0, v219
	v_add_u32_e32 v198, 0x18648, v219
	v_add_u32_e32 v220, 0x186c8, v219
	v_add_u32_e32 v224, 0x18660, v219
	v_add_u32_e32 v226, 0x186e0, v219
	v_add_u32_e32 v222, 0x18668, v219
	ds_read2_b32 v[178:179], v178 offset1:1
	ds_read2_b32 v[180:181], v180 offset1:1
	ds_read2_b32 v[182:183], v182 offset1:1
	ds_read2_b32 v[184:185], v184 offset1:1
	ds_read2_b32 v[186:187], v186 offset1:1
	ds_read2_b32 v[188:189], v188 offset1:1
	ds_read2_b32 v[190:191], v190 offset1:1
	ds_read2_b32 v[192:193], v192 offset1:1
	ds_read2_b32 v[194:195], v194 offset1:1
	ds_read2_b32 v[196:197], v196 offset1:1
	ds_read2_b32 v[198:199], v198 offset1:1
	ds_read2_b32 v[220:221], v220 offset1:1
	ds_read2_b32 v[222:223], v222 offset1:1
	ds_read2_b32 v[224:225], v224 offset1:1
	v_add_u32_e32 v219, 0x186e8, v219
	ds_read2_b32 v[226:227], v226 offset1:1
	ds_read2_b32 v[228:229], v219 offset1:1
	s_waitcnt lgkmcnt(5)
	v_pk_add_f32 v[106:107], v[106:107], v[198:199]
	s_waitcnt lgkmcnt(3)
	v_pk_add_f32 v[110:111], v[110:111], v[222:223]
	s_waitcnt lgkmcnt(2)
	v_pk_add_f32 v[108:109], v[108:109], v[224:225]
	v_pk_add_f32 v[104:105], v[104:105], v[194:195]
	v_pk_add_f32 v[102:103], v[102:103], v[190:191]
	v_pk_add_f32 v[100:101], v[100:101], v[186:187]
	v_pk_add_f32 v[98:99], v[98:99], v[182:183]
	v_pk_add_f32 v[96:97], v[96:97], v[178:179]
	s_waitcnt lgkmcnt(0)
	v_pk_add_f32 v[94:95], v[94:95], v[228:229]
	v_pk_add_f32 v[92:93], v[92:93], v[226:227]
	v_pk_add_f32 v[90:91], v[90:91], v[220:221]
	v_pk_add_f32 v[88:89], v[88:89], v[196:197]
	v_pk_add_f32 v[86:87], v[86:87], v[192:193]
	v_pk_add_f32 v[84:85], v[84:85], v[188:189]
	v_pk_add_f32 v[82:83], v[82:83], v[184:185]
	v_pk_add_f32 v[80:81], v[80:81], v[180:181]
.LBB0_375:
	s_nop 5
	v_max_f32_e32 v178, v96, v97
	s_nop 0
	v_max3_f32 v179, v98, v99, v81
	v_max3_f32 v178, v178, v80, v82
	v_max3_f32 v178, v178, v83, v100
	v_max3_f32 v179, v179, v102, v103
	v_max3_f32 v178, v178, v101, v84
	v_max3_f32 v179, v179, v86, v87
	v_max3_f32 v178, v178, v85, v104
	v_max3_f32 v179, v179, v106, v107
	v_max3_f32 v178, v178, v105, v88
	v_max3_f32 v179, v179, v90, v91
	v_max3_f32 v178, v178, v89, v108
	v_max3_f32 v179, v179, v110, v111
	v_max3_f32 v178, v178, v109, v92
	v_max3_f32 v179, v179, v94, v95
	v_max3_f32 v178, v178, v93, v179
	v_mov_b32_e32 v179, v178
	s_nop 1
	v_permlane32_swap_b32_e32 v178, v179
	v_max_f32_e32 v178, v178, v179
	v_cmp_lt_f32_e32 vcc, s41, v178
	s_cbranch_vccz .LBB0_377
; DI float ex2(float x) { return __builtin_amdgcn_exp2f(x); }
; DI void attn_unit(const Params& p, int bh, int qb, char* lds, float lam, int tid, int lane, int wid, const bool build_tab) {
;     ...
;             if (first || __builtin_amdgcn_ballot_w64(mx > 8.0f) != 0ull) {
;                 const float dl = first ? mx : __builtin_fmaxf(mx, 0.f);
;                 const float f = first ? 1.0f : ex2(-dl);
;                 l *= f; nm -= dl;
; #pragma unroll
;                 for (int i = 0; i < 16; ++i) { o[0][i] *= f; o[1][i] *= f; o[2][i] *= f; o[3][i] *= f; cinit[i] = nm; s0[i] -= dl; s1[i] -= dl; }
;             }
	v_max_f32_e32 v65, v178, v178
	v_max_f32_e32 v65, 0, v65
	v_exp_f32_e64 v66, -v65
	v_sub_f32_e32 v64, v64, v65
	v_sub_f32_e32 v111, v111, v65
	v_sub_f32_e32 v110, v110, v65
	v_pk_mul_f32 v[62:63], v[62:63], v[66:67] op_sel_hi:[1,0]
	v_pk_mul_f32 v[60:61], v[60:61], v[66:67] op_sel_hi:[1,0]
	v_pk_mul_f32 v[58:59], v[58:59], v[66:67] op_sel_hi:[1,0]
	v_pk_mul_f32 v[56:57], v[56:57], v[66:67] op_sel_hi:[1,0]
	v_pk_mul_f32 v[54:55], v[54:55], v[66:67] op_sel_hi:[1,0]
	v_pk_mul_f32 v[52:53], v[52:53], v[66:67] op_sel_hi:[1,0]
	v_pk_mul_f32 v[50:51], v[50:51], v[66:67] op_sel_hi:[1,0]
	v_pk_mul_f32 v[48:49], v[48:49], v[66:67] op_sel_hi:[1,0]
	v_pk_mul_f32 v[46:47], v[46:47], v[66:67] op_sel_hi:[1,0]
	v_pk_mul_f32 v[44:45], v[44:45], v[66:67] op_sel_hi:[1,0]
	v_pk_mul_f32 v[42:43], v[42:43], v[66:67] op_sel_hi:[1,0]
	v_pk_mul_f32 v[40:41], v[40:41], v[66:67] op_sel_hi:[1,0]
	v_pk_mul_f32 v[38:39], v[38:39], v[66:67] op_sel_hi:[1,0]
	v_pk_mul_f32 v[36:37], v[36:37], v[66:67] op_sel_hi:[1,0]
	v_pk_mul_f32 v[34:35], v[34:35], v[66:67] op_sel_hi:[1,0]
	v_pk_mul_f32 v[32:33], v[32:33], v[66:67] op_sel_hi:[1,0]
	v_pk_mul_f32 v[30:31], v[30:31], v[66:67] op_sel_hi:[1,0]
	v_pk_mul_f32 v[28:29], v[28:29], v[66:67] op_sel_hi:[1,0]
	v_pk_mul_f32 v[26:27], v[26:27], v[66:67] op_sel_hi:[1,0]
	v_pk_mul_f32 v[24:25], v[24:25], v[66:67] op_sel_hi:[1,0]
	v_pk_mul_f32 v[22:23], v[22:23], v[66:67] op_sel_hi:[1,0]
	v_pk_mul_f32 v[20:21], v[20:21], v[66:67] op_sel_hi:[1,0]
	v_pk_mul_f32 v[18:19], v[18:19], v[66:67] op_sel_hi:[1,0]
	v_pk_mul_f32 v[16:17], v[16:17], v[66:67] op_sel_hi:[1,0]
	v_pk_mul_f32 v[14:15], v[14:15], v[66:67] op_sel_hi:[1,0]
	v_pk_mul_f32 v[12:13], v[12:13], v[66:67] op_sel_hi:[1,0]
	v_pk_mul_f32 v[10:11], v[10:11], v[66:67] op_sel_hi:[1,0]
	v_pk_mul_f32 v[8:9], v[8:9], v[66:67] op_sel_hi:[1,0]
	v_pk_mul_f32 v[6:7], v[6:7], v[66:67] op_sel_hi:[1,0]
	v_pk_mul_f32 v[4:5], v[4:5], v[66:67] op_sel_hi:[1,0]
	v_pk_mul_f32 v[2:3], v[2:3], v[66:67] op_sel_hi:[1,0]
	v_pk_mul_f32 v[0:1], v[0:1], v[66:67] op_sel_hi:[1,0]
	v_sub_f32_e32 v109, v109, v65
	v_sub_f32_e32 v108, v108, v65
	v_sub_f32_e32 v107, v107, v65
	v_sub_f32_e32 v106, v106, v65
	v_sub_f32_e32 v105, v105, v65
	v_sub_f32_e32 v104, v104, v65
	v_sub_f32_e32 v103, v103, v65
	v_sub_f32_e32 v102, v102, v65
	v_sub_f32_e32 v101, v101, v65
	v_sub_f32_e32 v100, v100, v65
	v_sub_f32_e32 v99, v99, v65
	v_sub_f32_e32 v98, v98, v65
	v_sub_f32_e32 v97, v97, v65
	v_sub_f32_e32 v96, v96, v65
	v_sub_f32_e32 v95, v95, v65
	v_sub_f32_e32 v94, v94, v65
	v_sub_f32_e32 v93, v93, v65
	v_sub_f32_e32 v92, v92, v65
	v_sub_f32_e32 v91, v91, v65
	v_sub_f32_e32 v90, v90, v65
	v_sub_f32_e32 v89, v89, v65
	v_sub_f32_e32 v88, v88, v65
	v_sub_f32_e32 v87, v87, v65
	v_sub_f32_e32 v86, v86, v65
	v_sub_f32_e32 v85, v85, v65
	v_sub_f32_e32 v84, v84, v65
	v_sub_f32_e32 v83, v83, v65
	v_sub_f32_e32 v82, v82, v65
	v_sub_f32_e32 v81, v81, v65
	v_sub_f32_e32 v80, v80, v65
	v_mul_f32_e32 v176, v176, v66
	v_mov_b32_e32 v65, v64
	v_mov_b32_e32 v66, v64
	v_mov_b32_e32 v67, v64
	v_mov_b32_e32 v68, v64
	v_mov_b32_e32 v69, v64
	v_mov_b32_e32 v70, v64
	v_mov_b32_e32 v71, v64
	v_mov_b32_e32 v72, v64
	v_mov_b32_e32 v73, v64
	v_mov_b32_e32 v74, v64
	v_mov_b32_e32 v75, v64
	v_mov_b32_e32 v76, v64
	v_mov_b32_e32 v77, v64
	v_mov_b32_e32 v78, v64
	v_mov_b32_e32 v79, v64
; #define GLOAD(t_, slotoff_) do { const char* kb_ = KGc + ((size_t)(t_) << 14); const char* vb_ = VGc + ((size_t)(t_) << 14); \
;         const unsigned d_ = (unsigned)__builtin_amdgcn_readfirstlane((int)(ldsbase + (slotoff_) + wid * 1024)); \
;         GLDS16(kb_, d_); GLDS16(kb_ + 8192, d_ + 8192u); GLDS16(vb_, d_ + 16384u); GLDS16(vb_ + 8192, d_ + 24576u); } while (0)
; #define SCHEDB() __builtin_amdgcn_sched_barrier(0)
; #define LOADV(dst, ks_) do { _Pragma("unroll") for (int dvb = 0; dvb < 4; ++dvb) { dst[2 * dvb] = vtr(vp + dvb * 4096 + (ks_) * 1024); dst[2 * dvb + 1] = vtr(vp + dvb * 4096 + (ks_) * 1024 + 512); } } while (0)
; #define MF4(src, pfrag) do { _Pragma("unroll") for (int dvb = 0; dvb < 4; ++dvb) { \
;         const bf16x8 vf_ = __builtin_shufflevector(src[2 * dvb], src[2 * dvb + 1], 0, 1, 2, 3, 4, 5, 6, 7); o[dvb] = MFMA32(vf_, pfrag, o[dvb]); } } while (0)
; #define EXPQ(S, lo_, RS, PF) do { _Pragma("unroll") for (int i = lo_; i < lo_ + 8; ++i) { S[i] = ex2(S[i]); RS += S[i]; } \
;               u32x4 w_; w_.x = pk2(S[lo_], S[lo_ + 1]); w_.y = pk2(S[lo_ + 2], S[lo_ + 3]); w_.z = pk2(S[lo_ + 4], S[lo_ + 5]); w_.w = pk2(S[lo_ + 6], S[lo_ + 7]); PF = __builtin_bit_cast(bf16x8, w_); } while (0)
; DI void attn_unit(const Params& p, int bh, int qb, char* lds, float lam, int tid, int lane, int wid, const bool build_tab) {
;     ...
;             EXPQ(s0, 0, rs0, pf[0]);
;             LOADV(vb, 1);
;             MF4(va, pf[0]);
;             EXPQ(s0, 8, rs1, pf[1]);
;             LOADV(va, 2);
;             MF4(vb, pf[1]);
;             EXPQ(s1, 0, rs0, pf[2]);
;             LOADV(vb, 3);
;             MF4(va, pf[2]);
;             EXPQ(s1, 8, rs1, pf[3]);
;             MF4(vb, pf[3]);
;             l += rs0 + rs1;
;     ...
;         } else {
;             asm volatile("s_waitcnt vmcnt(0)" ::: "memory");
;             if (t + 2 < NT) GLOAD(t + 2, sn2);
;         }
;         SCHEDB();
;         __builtin_amdgcn_s_barrier();
;         SCHEDB();
;         { const int tmp = sc; sc = sn1; sn1 = sn2; sn2 = tmp; }
.LBB0_377:
.LBB0_379:
	ds_read_b64_tr_b16 v[230:231], v177 offset:21504
	ds_read_b64_tr_b16 v[232:233], v177 offset:22016
	ds_read_b64_tr_b16 v[234:235], v177 offset:25600
	ds_read_b64_tr_b16 v[236:237], v177 offset:26112
	v_exp_f32_e32 v178, v96
	v_exp_f32_e32 v180, v97
	v_exp_f32_e32 v182, v98
	v_exp_f32_e32 v184, v99
	v_exp_f32_e32 v186, v100
	v_exp_f32_e32 v188, v101
	v_exp_f32_e32 v190, v102
	v_exp_f32_e32 v192, v103
	v_cvt_pk_bf16_f32 v96, v178, v180
	v_cvt_pk_bf16_f32 v97, v182, v184
	v_cvt_pk_bf16_f32 v98, v186, v188
	v_cvt_pk_bf16_f32 v99, v190, v192
	ds_read_b64_tr_b16 v[100:101], v177 offset:17408
	ds_read_b64_tr_b16 v[102:103], v177 offset:17920
	s_waitcnt lgkmcnt(12)
	v_mfma_f32_32x32x16_bf16 v[48:63], v[140:143], v[96:99], v[48:63]
	ds_read_b64_tr_b16 v[238:239], v177 offset:29696
	ds_read_b64_tr_b16 v[240:241], v177 offset:30208
	v_exp_f32_e32 v179, v104
	v_exp_f32_e32 v181, v105
	v_exp_f32_e32 v183, v106
	v_add_f32_e32 v242, v180, v178
	s_waitcnt lgkmcnt(12)
	v_mfma_f32_32x32x16_bf16 v[32:47], v[136:139], v[96:99], v[32:47]
	v_exp_f32_e32 v185, v107
	v_exp_f32_e32 v187, v108
	v_exp_f32_e32 v189, v109
	v_add_f32_e32 v242, v182, v242
	s_waitcnt lgkmcnt(10)
	v_mfma_f32_32x32x16_bf16 v[16:31], v[132:135], v[96:99], v[16:31]
	v_exp_f32_e32 v191, v110
	v_exp_f32_e32 v193, v111
	v_add_f32_e32 v242, v184, v242
	v_add_f32_e32 v242, v186, v242
	ds_read_b64_tr_b16 v[104:105], v177 offset:18432
	ds_read_b64_tr_b16 v[106:107], v177 offset:18944
	ds_read_b64_tr_b16 v[108:109], v177 offset:19456
	ds_read_b64_tr_b16 v[110:111], v177 offset:19968
	s_waitcnt lgkmcnt(12)
	v_mfma_f32_32x32x16_bf16 v[0:15], v[128:131], v[96:99], v[0:15]
	ds_read_b64_tr_b16 v[128:129], v177 offset:26624
	ds_read_b64_tr_b16 v[130:131], v177 offset:27136
	v_cvt_pk_bf16_f32 v96, v179, v181
	v_cvt_pk_bf16_f32 v97, v183, v185
	v_cvt_pk_bf16_f32 v98, v187, v189
	v_cvt_pk_bf16_f32 v99, v191, v193
	v_exp_f32_e32 v140, v84
	v_exp_f32_e32 v142, v85
	s_waitcnt lgkmcnt(8)
	v_mfma_f32_32x32x16_bf16 v[48:63], v[100:103], v[96:99], v[48:63]
	v_exp_f32_e32 v194, v86
	v_exp_f32_e32 v196, v87
	v_add_f32_e32 v242, v188, v242
	ds_read_b64_tr_b16 v[84:85], v177 offset:22528
	ds_read_b64_tr_b16 v[86:87], v177 offset:23040
	v_exp_f32_e32 v136, v82
	s_waitcnt lgkmcnt(14)
	v_mfma_f32_32x32x16_bf16 v[32:47], v[230:233], v[96:99], v[32:47]
	ds_read_b64_tr_b16 v[230:231], v177 offset:23552
	ds_read_b64_tr_b16 v[232:233], v177 offset:24064
	v_exp_f32_e32 v138, v83
	v_exp_f32_e32 v132, v80
	v_exp_f32_e32 v134, v81
	v_add_f32_e32 v242, v190, v242
	s_waitcnt lgkmcnt(14)
	v_mfma_f32_32x32x16_bf16 v[16:31], v[234:237], v[96:99], v[16:31]
	ds_read_b64_tr_b16 v[234:235], v177 offset:27648
	ds_read_b64_tr_b16 v[236:237], v177 offset:28160
	v_cvt_pk_bf16_f32 v80, v132, v134
	v_cvt_pk_bf16_f32 v81, v136, v138
	v_cvt_pk_bf16_f32 v82, v140, v142
	v_cvt_pk_bf16_f32 v83, v194, v196
	v_exp_f32_e32 v133, v88
	v_exp_f32_e32 v135, v89
	s_waitcnt lgkmcnt(12)
	v_mfma_f32_32x32x16_bf16 v[0:15], v[238:241], v[96:99], v[0:15]
	ds_read_b64_tr_b16 v[238:239], v177 offset:31744
	ds_read_b64_tr_b16 v[240:241], v177 offset:32256
	v_exp_f32_e32 v137, v90
	v_exp_f32_e32 v139, v91
	v_add_f32_e32 v242, v192, v242
	ds_read_b64_tr_b16 v[88:89], v177 offset:30720
	ds_read_b64_tr_b16 v[90:91], v177 offset:31232
	v_exp_f32_e32 v141, v92
	s_waitcnt lgkmcnt(14)
	v_mfma_f32_32x32x16_bf16 v[48:63], v[104:107], v[80:83], v[48:63]
	v_exp_f32_e32 v143, v93
	v_exp_f32_e32 v195, v94
	v_exp_f32_e32 v197, v95
	v_add_f32_e32 v242, v132, v242
	s_waitcnt lgkmcnt(8)
	v_mfma_f32_32x32x16_bf16 v[32:47], v[84:87], v[80:83], v[32:47]
	v_add_f32_e32 v243, v181, v179
	v_add_f32_e32 v242, v134, v242
	v_add_f32_e32 v243, v183, v243
	v_add_f32_e32 v242, v136, v242
	v_add_f32_e32 v243, v185, v243
	v_add_f32_e32 v242, v138, v242
	s_waitcnt lgkmcnt(10)
	v_mfma_f32_32x32x16_bf16 v[16:31], v[128:131], v[80:83], v[16:31]
	v_add_f32_e32 v243, v187, v243
	v_add_f32_e32 v242, v140, v242
	v_add_f32_e32 v243, v189, v243
	v_add_f32_e32 v242, v142, v242
	v_add_f32_e32 v243, v191, v243
	v_add_f32_e32 v242, v194, v242
	v_add_f32_e32 v243, v193, v243
	s_waitcnt lgkmcnt(0)
	v_mfma_f32_32x32x16_bf16 v[0:15], v[88:91], v[80:83], v[0:15]
	v_cvt_pk_bf16_f32 v80, v133, v135
	v_cvt_pk_bf16_f32 v81, v137, v139
	v_cvt_pk_bf16_f32 v82, v141, v143
	v_cvt_pk_bf16_f32 v83, v195, v197
	v_add_f32_e32 v242, v196, v242
	v_add_f32_e32 v243, v133, v243
	s_waitcnt lgkmcnt(12)
	v_mfma_f32_32x32x16_bf16 v[48:63], v[108:111], v[80:83], v[48:63]
	v_add_f32_e32 v243, v135, v243
	v_add_f32_e32 v243, v137, v243
	s_waitcnt lgkmcnt(6)
	v_mfma_f32_32x32x16_bf16 v[32:47], v[230:233], v[80:83], v[32:47]
	v_add_f32_e32 v243, v139, v243
	v_add_f32_e32 v243, v141, v243
	s_waitcnt lgkmcnt(4)
	v_mfma_f32_32x32x16_bf16 v[16:31], v[234:237], v[80:83], v[16:31]
	v_add_f32_e32 v243, v143, v243
	v_add_f32_e32 v243, v195, v243
	s_waitcnt lgkmcnt(2)
	v_mfma_f32_32x32x16_bf16 v[0:15], v[238:241], v[80:83], v[0:15]
	v_add_f32_e32 v243, v197, v243
	v_add_f32_e32 v242, v242, v243
	v_add_f32_e32 v176, v176, v242
	s_add_i32 s96, s68, s61
	v_add3_u32 v244, s96, v204, v205
	ds_read_b128 v[178:181], v244
	ds_read_b128 v[182:185], v244 offset:512
	ds_read_b128 v[186:189], v244 offset:2048
	ds_read_b128 v[190:193], v244 offset:2560
	s_waitcnt vmcnt(0)

; __global__ __launch_bounds__(NTHREADS, 2) void hymba_mega(Params p) {
	.amdhsa_kernel _Z10hymba_mega6Params
		.amdhsa_group_segment_fixed_size 0
		.amdhsa_private_segment_fixed_size 0
		.amdhsa_kernarg_size 392
		.amdhsa_user_sgpr_count 2
		.amdhsa_user_sgpr_dispatch_ptr 0
		.amdhsa_user_sgpr_queue_ptr 0
		.amdhsa_user_sgpr_kernarg_segment_ptr 1
		.amdhsa_user_sgpr_dispatch_id 0
		.amdhsa_user_sgpr_kernarg_preload_length 0
		.amdhsa_user_sgpr_kernarg_preload_offset 0
		.amdhsa_user_sgpr_private_segment_size 0
		.amdhsa_uses_dynamic_stack 0
		.amdhsa_enable_private_segment 0
		.amdhsa_system_sgpr_workgroup_id_x 1
		.amdhsa_system_sgpr_workgroup_id_y 0
		.amdhsa_system_sgpr_workgroup_id_z 0
		.amdhsa_system_sgpr_workgroup_info 0
		.amdhsa_system_vgpr_workitem_id 2
		.amdhsa_next_free_vgpr 254
		.amdhsa_next_free_sgpr 98
		.amdhsa_accum_offset 256
		.amdhsa_reserve_vcc 1
		.amdhsa_float_round_mode_32 0
		.amdhsa_float_round_mode_16_64 0
		.amdhsa_float_denorm_mode_32 3
		.amdhsa_float_denorm_mode_16_64 3
		.amdhsa_dx10_clamp 1
		.amdhsa_ieee_mode 1
		.amdhsa_fp16_overflow 0
		.amdhsa_tg_split 0
		.amdhsa_exception_fp_ieee_invalid_op 0
		.amdhsa_exception_fp_denorm_src 0
		.amdhsa_exception_fp_ieee_div_zero 0
		.amdhsa_exception_fp_ieee_overflow 0
		.amdhsa_exception_fp_ieee_underflow 0
		.amdhsa_exception_fp_ieee_inexact 0
		.amdhsa_exception_int_div_zero 0
	.end_amdhsa_kernel

; __global__ __launch_bounds__(NTHREADS, 2) void hymba_mega(Params p) {
amdhsa.kernels:
  - .agpr_count:     0
    .args:
      - .offset:         0
        .size:           136
        .value_kind:     by_value
      - .offset:         136
        .size:           4
        .value_kind:     hidden_block_count_x
      - .offset:         140
        .size:           4
        .value_kind:     hidden_block_count_y
      - .offset:         144
        .size:           4
        .value_kind:     hidden_block_count_z
      - .offset:         148
        .size:           2
        .value_kind:     hidden_group_size_x
      - .offset:         150
        .size:           2
        .value_kind:     hidden_group_size_y
      - .offset:         152
        .size:           2
        .value_kind:     hidden_group_size_z
      - .offset:         154
        .size:           2
        .value_kind:     hidden_remainder_x
      - .offset:         156
        .size:           2
        .value_kind:     hidden_remainder_y
      - .offset:         158
        .size:           2
        .value_kind:     hidden_remainder_z
      - .offset:         176
        .size:           8
        .value_kind:     hidden_global_offset_x
      - .offset:         184
        .size:           8
        .value_kind:     hidden_global_offset_y
      - .offset:         192
        .size:           8
        .value_kind:     hidden_global_offset_z
      - .offset:         200
        .size:           2
        .value_kind:     hidden_grid_dims
      - .offset:         224
        .size:           8
        .value_kind:     hidden_multigrid_sync_arg
      - .offset:         256
        .size:           4
        .value_kind:     hidden_dynamic_lds_size
    .group_segment_fixed_size: 0
    .kernarg_segment_align: 8
    .kernarg_segment_size: 392
    .language:       OpenCL C
    .language_version:
      - 2
      - 0
    .max_flat_workgroup_size: 512
    .name:           _Z10hymba_mega6Params
    .private_segment_fixed_size: 0
    .sgpr_count:     104
    .sgpr_spill_count: 0
    .symbol:         _Z10hymba_mega6Params.kd
    .uniform_work_group_size: 1
    .uses_dynamic_stack: false
    .vgpr_count:     254
    .vgpr_spill_count: 0
    .wavefront_size: 64
